# B1: prev-token r/k/v from neighbour lane (DPP) + LDS stage instead of reloads; queue hand-off with DS ops instead of flat ops (no store drain at item boundaries)
# baseline (speedup 1.0000x reference)
.LBB0_323:
	s_or_b64 exec, exec, s[0:1]
	s_add_i32 s24, 0, 0x24008
	s_mov_b64 s[0:1], src_shared_base
	s_cmp_lg_u32 s24, -1
	s_cselect_b32 s0, s24, 0
	s_cselect_b32 s1, s1, 0
	v_mov_b32_e32 v2, s0
	v_mov_b32_e32 v3, s1
	s_waitcnt lgkmcnt(0)
	s_barrier
	flat_load_dword v206, v[2:3] sc0 sc1
	s_waitcnt vmcnt(0)
	s_movk_i32 s0, 0x84c
	s_waitcnt lgkmcnt(0)
	v_cmp_gt_i32_e32 vcc, s0, v206
	s_and_saveexec_b64 s[46:47], vcc
	s_cbranch_execz .LBB0_499
	s_lshl_b64 s[0:1], s[36:37], 15
	v_lshlrev_b64 v[0:1], 6, v[0:1]
	v_lshl_add_u64 v[0:1], v[0:1], 0, s[0:1]
	v_readlane_b32 s0, v214, 33
	v_lshlrev_b64 v[0:1], 1, v[0:1]
	v_readlane_b32 s1, v214, 34
	s_mov_b64 s[22:23], s[36:37]
	s_lshl_b32 s37, s22, 5
	v_lshl_add_u64 v[126:127], s[0:1], 0, v[0:1]
	v_readlane_b32 s0, v214, 35
	v_readlane_b32 s1, v214, 36
	s_lshl_b64 s[30:31], s[22:23], 3
	s_lshl_b64 s[60:61], s[22:23], 7
	v_lshl_add_u64 v[128:129], s[0:1], 0, v[0:1]
	s_lshl_b32 s0, s22, 8
	s_ashr_i32 s1, s0, 31
	s_lshl_b32 s72, s22, 2
	s_lshl_b32 s33, s22, 7
	s_lshl_b64 s[0:1], s[0:1], 2
	s_add_u32 s34, s12, s0
	s_addc_u32 s35, s13, s1
	s_mov_b64 s[0:1], s[54:55]
	s_mov_b64 s[28:29], s[46:47]
	v_readlane_b32 s40, v213, 42
	s_mul_i32 s20, s22, 0xd0000
	v_readlane_b32 s48, v213, 50
	s_mul_hi_i32 s2, s22, 0xd0000
	v_readlane_b32 s49, v213, 51
	v_readlane_b32 s54, v213, 56
	v_readlane_b32 s55, v213, 57
	s_add_u32 s64, s48, s20
	v_readlane_b32 s52, v213, 54
	s_mov_b64 s[54:55], s[0:1]
	s_addc_u32 s65, s49, s2
	s_mul_i32 s1, s22, 0x1e000
	v_readlane_b32 s2, v213, 36
	v_readlane_b32 s53, v213, 55
	s_mul_hi_i32 s0, s22, 0x1e000
	s_add_u32 s52, s2, s1
	v_readlane_b32 s1, v213, 37
	v_readlane_b32 s46, v213, 48
	s_addc_u32 s53, s1, s0
	s_mul_i32 s1, s22, 0x1e0000
	v_readlane_b32 s47, v213, 49
	s_mul_hi_i32 s0, s22, 0x1e0000
	s_add_u32 s20, s46, s1
	s_addc_u32 s21, s47, s0
	v_writelane_b32 v212, s20, 45
	v_readlane_b32 s2, v213, 62
	v_readlane_b32 s50, v213, 52
	v_writelane_b32 v212, s21, 46
	s_add_u32 s20, s92, s1
	s_addc_u32 s21, s93, s0
	v_writelane_b32 v212, s20, 43
	s_mul_i32 s1, s22, 0xd000
	s_mul_hi_i32 s0, s22, 0xd000
	v_writelane_b32 v212, s21, 44
	s_add_u32 s20, s2, s1
	v_readlane_b32 s1, v213, 63
	v_readlane_b32 s51, v213, 53
	s_addc_u32 s21, s1, s0
	s_mov_b64 s[50:51], s[34:35]
	s_mov_b64 s[48:49], s[30:31]
	s_mov_b32 s66, s60
	s_mov_b32 s67, s61
	s_mov_b64 s[46:47], s[28:29]
	v_writelane_b32 v212, s20, 47
	v_mov_b32_e32 v205, 0
	s_mov_b64 s[58:59], 0
	v_readlane_b32 s41, v213, 43
	v_readlane_b32 s42, v213, 44
	v_readlane_b32 s43, v213, 45
	v_readlane_b32 s44, v213, 46
	v_readlane_b32 s45, v213, 47
	v_writelane_b32 v212, s21, 48
	v_lshrrev_b32_e32 v218, 6, v133
	v_and_b32_e32 v217, 15, v192
	v_readfirstlane_b32 s0, v218
	v_lshlrev_b32_e32 v217, 7, v217
	v_lshrrev_b32_e32 v219, 4, v192
	v_lshl_add_u32 v217, v219, 4, v217
	s_mul_i32 s0, s0, 0x3000
	s_addk_i32 s0, 0x6000
	v_mov_b32_e32 v218, v217
	v_mov_b32_e32 v219, 0
	v_lshl_add_u64 v[218:219], v[126:127], 0, v[218:219]
	s_add_i32 m0, s0, 0x0
	s_nop 0
	global_load_lds_dwordx4 v[218:219], off
	s_add_i32 m0, s0, 0x7c0
	s_nop 0
	global_load_lds_dwordx4 v[218:219], off offset:64
	s_add_i32 m0, s0, 0x800
	s_nop 0
	global_load_lds_dwordx4 v[218:219], off offset:2048
	s_add_i32 m0, s0, 0xfc0
	s_nop 0
	global_load_lds_dwordx4 v[218:219], off offset:2112
	v_add_co_u32_e32 v218, vcc, 0x1000, v218
	s_nop 1
	v_addc_co_u32_e32 v219, vcc, 0, v219, vcc
	s_add_i32 m0, s0, 0x2000
	s_nop 0
	global_load_lds_dwordx4 v[218:219], off
	s_add_i32 m0, s0, 0x27c0
	s_nop 0
	global_load_lds_dwordx4 v[218:219], off offset:64
	global_load_dwordx4 a[0:3], v[218:219], off offset:2048
	global_load_dwordx4 a[8:11], v[218:219], off offset:2112
	v_mov_b32_e32 v218, v217
	v_mov_b32_e32 v219, 0
	v_lshl_add_u64 v[218:219], v[128:129], 0, v[218:219]
	s_add_i32 m0, s0, 0x400
	s_nop 0
	global_load_lds_dwordx4 v[218:219], off
	s_add_i32 m0, s0, 0xbc0
	s_nop 0
	global_load_lds_dwordx4 v[218:219], off offset:64
	s_add_i32 m0, s0, 0xc00
	s_nop 0
	global_load_lds_dwordx4 v[218:219], off offset:2048
	s_add_i32 m0, s0, 0x13c0
	s_nop 0
	global_load_lds_dwordx4 v[218:219], off offset:2112
	v_add_co_u32_e32 v218, vcc, 0x1000, v218
	s_nop 1
	v_addc_co_u32_e32 v219, vcc, 0, v219, vcc
	s_add_i32 m0, s0, 0x2400
	s_nop 0
	global_load_lds_dwordx4 v[218:219], off
	s_add_i32 m0, s0, 0x2bc0
	s_nop 0
	global_load_lds_dwordx4 v[218:219], off offset:64
	global_load_dwordx4 a[4:7], v[218:219], off offset:2048
	global_load_dwordx4 a[12:15], v[218:219], off offset:2112
	v_lshlrev_b32_e32 v217, 4, v192
	v_add_u32_e32 v217, s0, v217
	v_lshrrev_b32_e32 v218, 6, v133
	v_lshlrev_b32_e32 v218, 7, v218
	v_lshrrev_b32_e32 v219, 4, v192
	v_lshl_add_u32 v218, v219, 3, v218
	v_add_u32_e32 v218, 0x1200, v218
	s_branch .LBB0_326
.LBB0_325:
	s_or_b64 exec, exec, s[0:1]
	s_mov_b64 s[0:1], src_shared_base
	s_cmp_lg_u32 s24, -1
	s_cselect_b32 s0, s24, 0
	s_cselect_b32 s1, s1, 0
	v_mov_b32_e32 v0, s0
	v_mov_b32_e32 v1, s1
	s_waitcnt lgkmcnt(0)
	s_barrier
	ds_read_b32 v206, v0
	s_nop 0
	s_movk_i32 s0, 0x84b
	s_waitcnt lgkmcnt(0)
	v_cmp_lt_i32_e32 vcc, s0, v206
	s_or_b64 s[58:59], vcc, s[58:59]
	s_andn2_b64 exec, exec, s[58:59]
	s_cbranch_execz .LBB0_499

.LBB0_405:
	s_andn2_saveexec_b64 s[56:57], s[96:97]
	s_cbranch_execz .LBB0_497
	v_mov_b32_e32 v130, v133
	v_readlane_b32 s0, v214, 12
	v_lshlrev_b32_e32 v132, 4, v206
	v_and_b32_e32 v98, 15, v130
	v_readlane_b32 s1, v214, 13
	v_or_b32_e32 v134, v98, v132
	v_and_b32_e32 v150, 0xffffffc0, v130
	s_waitcnt lgkmcnt(0)
	v_mov_b64_e32 v[4:5], s[0:1]
	v_bfe_u32 v207, v130, 4, 2
	v_mad_i64_i32 v[0:1], s[0:1], v134, s83, v[4:5]
	v_ashrrev_i32_e32 v151, 31, v150
	v_lshl_add_u64 v[2:3], v[150:151], 1, v[0:1]
	v_lshlrev_b32_e32 v0, 3, v207
	v_mov_b32_e32 v1, v65
	v_lshl_add_u64 v[2:3], v[2:3], 0, v[0:1]
	global_load_dwordx2 v[146:147], v[2:3], off offset:1024
	global_load_dwordx2 v[144:145], v[2:3], off offset:1056
	global_load_dwordx2 v[142:143], v[2:3], off offset:1088
	global_load_dwordx2 v[140:141], v[2:3], off offset:1120
	global_load_dwordx2 v[72:73], v[2:3], off offset:2048
	global_load_dwordx2 v[94:95], v[2:3], off offset:2080
	global_load_dwordx2 v[120:121], v[2:3], off offset:2112
	global_load_dwordx2 v[138:139], v[2:3], off offset:2144
	global_load_dwordx2 v[70:71], v[2:3], off offset:3072
	global_load_dwordx2 v[96:97], v[2:3], off offset:3104
	global_load_dwordx2 v[118:119], v[2:3], off offset:3136
	global_load_dwordx2 v[136:137], v[2:3], off offset:3168
	v_and_b32_e32 v2, 0x7f, v130
	v_lshlrev_b32_e32 v64, 2, v2
	v_lshl_add_u64 v[6:7], s[74:75], 0, v[64:65]
	v_add_co_u32_e32 v6, vcc, s73, v6
	s_nop 1
	v_addc_co_u32_e32 v7, vcc, 0, v7, vcc
	s_barrier
	global_load_dword v3, v[6:7], off offset:2048
	v_and_b32_e32 v1, 0x7f, v206
	v_add_u32_e32 v131, 0x200, v130
	s_movk_i32 s0, 0x400
	v_cmp_gt_i32_e64 s[42:43], s0, v206
	s_movk_i32 s0, 0x3ff
	v_cmp_lt_i32_e64 s[40:41], s0, v206
	v_cmp_eq_u32_e64 s[44:45], 0, v1
	v_readlane_b32 s20, v214, 12
	v_readlane_b32 s21, v214, 13
	v_lshlrev_b32_e32 v4, 1, v2
	v_ashrrev_i32_e32 v6, 7, v130
	v_add_u32_e32 v8, v6, v132
	s_movk_i32 s2, 0x1000
	v_add_u32_e32 v9, 4, v8
	v_add_u32_e32 v10, 8, v8
	v_add_u32_e32 v11, 12, v8
	v_mul_lo_u32 v12, v8, s83
	v_add3_u32 v12, v12, v4, s2
	global_load_ushort v16, v12, s[20:21]
	v_mul_lo_u32 v13, v9, s83
	v_add3_u32 v13, v13, v4, s2
	global_load_ushort v17, v13, s[20:21]
	v_mul_lo_u32 v14, v10, s83
	v_add3_u32 v14, v14, v4, s2
	global_load_ushort v18, v14, s[20:21]
	v_mul_lo_u32 v15, v11, s83
	v_add3_u32 v15, v15, v4, s2
	global_load_ushort v19, v15, s[20:21]
	v_readfirstlane_b32 s0, v130
	s_cmpk_ge_u32 s0, 0x180
	s_cbranch_scc1 .Lpc_nostage
	v_add_u32_e32 v29, -1, v132
	v_max_i32_e32 v29, 0, v29
	v_mul_lo_u32 v29, v29, s83
	v_lshl_add_u32 v29, v130, 3, v29
	global_load_dwordx2 v[30:31], v29, s[20:21] offset:1024
.Lpc_nostage:
	s_and_b64 vcc, exec, s[40:41]
	s_cbranch_vccz .Lpc_prompt
	s_movk_i32 s2, 0x1800
	v_add_u32_e32 v20, 0xffffc000, v8
	v_mul_lo_u32 v20, v20, s86
	v_add3_u32 v20, v20, v64, s2
	global_load_dword v24, v20, s[64:65]
	v_add_u32_e32 v21, 0xffffc000, v9
	v_mul_lo_u32 v21, v21, s86
	v_add3_u32 v21, v21, v64, s2
	global_load_dword v25, v21, s[64:65]
	v_add_u32_e32 v22, 0xffffc000, v10
	v_mul_lo_u32 v22, v22, s86
	v_add3_u32 v22, v22, v64, s2
	global_load_dword v26, v22, s[64:65]
	v_add_u32_e32 v23, 0xffffc000, v11
	v_mul_lo_u32 v23, v23, s86
	v_add3_u32 v23, v23, v64, s2
	global_load_dword v27, v23, s[64:65]
	s_waitcnt vmcnt(0)
	s_branch .Lpc_join

.Lpc_join:
	v_lshlrev_b32_e32 v16, 16, v16
	v_lshlrev_b32_e32 v17, 16, v17
	v_lshlrev_b32_e32 v18, 16, v18
	v_lshlrev_b32_e32 v19, 16, v19
	v_sub_f32_e32 v24, v24, v16
	v_sub_f32_e32 v25, v25, v17
	v_sub_f32_e32 v26, v26, v18
	v_sub_f32_e32 v27, v27, v19
	v_fmac_f32_e32 v16, v3, v24
	v_fmac_f32_e32 v17, v3, v25
	v_fmac_f32_e32 v18, v3, v26
	v_fmac_f32_e32 v19, v3, v27
	v_mul_u32_u24_e32 v28, 0x90, v6
	v_add_u32_e32 v28, v28, v4
	s_cmpk_ge_u32 s0, 0x180
	s_cbranch_scc1 .Lpc_nostage2
	v_lshlrev_b32_e32 v29, 3, v130
	ds_write_b64 v29, v[30:31] offset:4608
.Lpc_nostage2:
	s_bitcmp1_b32 s0, 6
	s_cbranch_scc1 .Lpc_ad
	v_add_f32_e32 v5, v16, v16
	v_mul_f32_e32 v5, 0x3fb8aa3b, v5
	v_exp_f32_e32 v5, v5
	s_nop 0
	v_add_f32_e32 v5, 1.0, v5
	v_div_scale_f32 v7, s[22:23], v5, v5, 2.0
	v_rcp_f32_e32 v29, v7
	v_div_scale_f32 v9, vcc, 2.0, v5, 2.0
	v_fma_f32 v10, -v7, v29, 1.0
	v_fmac_f32_e32 v29, v10, v29
	v_mul_f32_e32 v10, v9, v29
	v_fma_f32 v11, -v7, v10, v9
	v_fmac_f32_e32 v10, v11, v29
	v_fma_f32 v7, -v7, v10, v9
	v_div_fmas_f32 v7, v7, v29, v10
	v_div_fixup_f32 v5, v7, v5, 2.0
	v_sub_f32_e32 v5, 1.0, v5
	v_bfe_u32 v7, v5, 16, 1
	v_add3_u32 v5, v5, v7, s27
	ds_write_b16_d16_hi v28, v5 offset:0
	v_add_f32_e32 v5, v17, v17
	v_mul_f32_e32 v5, 0x3fb8aa3b, v5
	v_exp_f32_e32 v5, v5
	s_nop 0
	v_add_f32_e32 v5, 1.0, v5
	v_div_scale_f32 v7, s[22:23], v5, v5, 2.0
	v_rcp_f32_e32 v29, v7
	v_div_scale_f32 v9, vcc, 2.0, v5, 2.0
	v_fma_f32 v10, -v7, v29, 1.0
	v_fmac_f32_e32 v29, v10, v29
	v_mul_f32_e32 v10, v9, v29
	v_fma_f32 v11, -v7, v10, v9
	v_fmac_f32_e32 v10, v11, v29
	v_fma_f32 v7, -v7, v10, v9
	v_div_fmas_f32 v7, v7, v29, v10
	v_div_fixup_f32 v5, v7, v5, 2.0
	v_sub_f32_e32 v5, 1.0, v5
	v_bfe_u32 v7, v5, 16, 1
	v_add3_u32 v5, v5, v7, s27
	ds_write_b16_d16_hi v28, v5 offset:576
	v_add_f32_e32 v5, v18, v18
	v_mul_f32_e32 v5, 0x3fb8aa3b, v5
	v_exp_f32_e32 v5, v5
	s_nop 0
	v_add_f32_e32 v5, 1.0, v5
	v_div_scale_f32 v7, s[22:23], v5, v5, 2.0
	v_rcp_f32_e32 v29, v7
	v_div_scale_f32 v9, vcc, 2.0, v5, 2.0
	v_fma_f32 v10, -v7, v29, 1.0
	v_fmac_f32_e32 v29, v10, v29
	v_mul_f32_e32 v10, v9, v29
	v_fma_f32 v11, -v7, v10, v9
	v_fmac_f32_e32 v10, v11, v29
	v_fma_f32 v7, -v7, v10, v9
	v_div_fmas_f32 v7, v7, v29, v10
	v_div_fixup_f32 v5, v7, v5, 2.0
	v_sub_f32_e32 v5, 1.0, v5
	v_bfe_u32 v7, v5, 16, 1
	v_add3_u32 v5, v5, v7, s27
	ds_write_b16_d16_hi v28, v5 offset:1152
	v_add_f32_e32 v5, v19, v19
	v_mul_f32_e32 v5, 0x3fb8aa3b, v5
	v_exp_f32_e32 v5, v5
	s_nop 0
	v_add_f32_e32 v5, 1.0, v5
	v_div_scale_f32 v7, s[22:23], v5, v5, 2.0
	v_rcp_f32_e32 v29, v7
	v_div_scale_f32 v9, vcc, 2.0, v5, 2.0
	v_fma_f32 v10, -v7, v29, 1.0
	v_fmac_f32_e32 v29, v10, v29
	v_mul_f32_e32 v10, v9, v29
	v_fma_f32 v11, -v7, v10, v9
	v_fmac_f32_e32 v10, v11, v29
	v_fma_f32 v7, -v7, v10, v9
	v_div_fmas_f32 v7, v7, v29, v10
	v_div_fixup_f32 v5, v7, v5, 2.0
	v_sub_f32_e32 v5, 1.0, v5
	v_bfe_u32 v7, v5, 16, 1
	v_add3_u32 v5, v5, v7, s27
	ds_write_b16_d16_hi v28, v5 offset:1728
	s_branch .Lpc_done

.LBB0_452:
	s_or_saveexec_b64 s[20:21], s[20:21]
	s_xor_b64 s[22:23], s[42:43], -1
	s_or_b64 s[42:43], s[22:23], s[0:1]
	v_readlane_b32 s0, v214, 12
	v_readlane_b32 s1, v214, 13
	v_add_u32_e32 v81, -1, v134
	s_nop 0
	v_mov_b64_e32 v[82:83], s[0:1]
	v_mad_i64_i32 v[164:165], s[0:1], v81, s83, v[82:83]
	s_xor_b64 exec, exec, s[20:21]
	s_cbranch_execz .LBB0_456
	ds_read_b64 v[18:19], v218 offset:0
	ds_read_b64 v[58:59], v218 offset:1024
	ds_read_b64 v[62:63], v218 offset:2048
	s_waitcnt lgkmcnt(0)
	v_mov_b32_dpp v18, v146 row_shr:1 row_mask:0xf bank_mask:0xf
	v_mov_b32_dpp v19, v147 row_shr:1 row_mask:0xf bank_mask:0xf
	v_mov_b32_dpp v58, v72 row_shr:1 row_mask:0xf bank_mask:0xf
	v_mov_b32_dpp v59, v73 row_shr:1 row_mask:0xf bank_mask:0xf
	v_mov_b32_dpp v62, v70 row_shr:1 row_mask:0xf bank_mask:0xf
	v_mov_b32_dpp v63, v71 row_shr:1 row_mask:0xf bank_mask:0xf
	s_nop 1
	v_lshlrev_b32_e32 v16, 16, v18
	v_and_b32_e32 v17, 0xffff0000, v18
	v_lshlrev_b32_e32 v18, 16, v19
	v_and_b32_e32 v19, 0xffff0000, v19
	v_lshlrev_b32_e32 v56, 16, v58
	v_and_b32_e32 v57, 0xffff0000, v58
	v_lshlrev_b32_e32 v58, 16, v59
	v_and_b32_e32 v59, 0xffff0000, v59
	v_lshlrev_b32_e32 v60, 16, v62
	v_and_b32_e32 v61, 0xffff0000, v62
	v_lshlrev_b32_e32 v62, 16, v63
	v_and_b32_e32 v63, 0xffff0000, v63
	s_mov_b64 s[0:1], exec
	s_andn2_b64 exec, exec, s[42:43]
	v_mov_b32_e32 v19, 0
	v_mov_b32_e32 v18, 0
	v_mov_b32_e32 v17, 0
	v_mov_b32_e32 v16, 0
	v_mov_b32_e32 v59, 0
	v_mov_b32_e32 v58, 0
	v_mov_b32_e32 v57, 0
	v_mov_b32_e32 v56, 0
	v_mov_b32_e32 v63, 0
	v_mov_b32_e32 v62, 0
	v_mov_b32_e32 v61, 0
	v_mov_b32_e32 v60, 0
	s_mov_b64 exec, s[0:1]

.LBB0_458:
	s_andn2_saveexec_b64 s[0:1], s[0:1]
	s_cbranch_execz .LBB0_462
	ds_read_b64 v[58:59], v218 offset:32
	ds_read_b64 v[84:85], v218 offset:1056
	ds_read_b64 v[88:89], v218 offset:2080
	s_waitcnt lgkmcnt(0)
	v_mov_b32_dpp v58, v144 row_shr:1 row_mask:0xf bank_mask:0xf
	v_mov_b32_dpp v59, v145 row_shr:1 row_mask:0xf bank_mask:0xf
	v_mov_b32_dpp v84, v94 row_shr:1 row_mask:0xf bank_mask:0xf
	v_mov_b32_dpp v85, v95 row_shr:1 row_mask:0xf bank_mask:0xf
	v_mov_b32_dpp v88, v96 row_shr:1 row_mask:0xf bank_mask:0xf
	v_mov_b32_dpp v89, v97 row_shr:1 row_mask:0xf bank_mask:0xf
	s_nop 1
	v_lshlrev_b32_e32 v56, 16, v58
	v_and_b32_e32 v57, 0xffff0000, v58
	v_lshlrev_b32_e32 v58, 16, v59
	v_and_b32_e32 v59, 0xffff0000, v59
	v_lshlrev_b32_e32 v82, 16, v84
	v_and_b32_e32 v83, 0xffff0000, v84
	v_lshlrev_b32_e32 v84, 16, v85
	v_and_b32_e32 v85, 0xffff0000, v85
	v_lshlrev_b32_e32 v86, 16, v88
	v_and_b32_e32 v87, 0xffff0000, v88
	v_lshlrev_b32_e32 v88, 16, v89
	v_and_b32_e32 v89, 0xffff0000, v89
	s_mov_b64 s[20:21], exec
	s_andn2_b64 exec, exec, s[42:43]
	v_mov_b32_e32 v59, 0
	v_mov_b32_e32 v58, 0
	v_mov_b32_e32 v57, 0
	v_mov_b32_e32 v56, 0
	v_mov_b32_e32 v85, 0
	v_mov_b32_e32 v84, 0
	v_mov_b32_e32 v83, 0
	v_mov_b32_e32 v82, 0
	v_mov_b32_e32 v89, 0
	v_mov_b32_e32 v88, 0
	v_mov_b32_e32 v87, 0
	v_mov_b32_e32 v86, 0
	s_mov_b64 exec, s[20:21]

.LBB0_464:
	s_andn2_saveexec_b64 s[0:1], s[0:1]
	s_cbranch_execz .LBB0_468
	ds_read_b64 v[84:85], v218 offset:64
	ds_read_b64 v[108:109], v218 offset:1088
	ds_read_b64 v[116:117], v218 offset:2112
	s_waitcnt lgkmcnt(0)
	v_mov_b32_dpp v84, v142 row_shr:1 row_mask:0xf bank_mask:0xf
	v_mov_b32_dpp v85, v143 row_shr:1 row_mask:0xf bank_mask:0xf
	v_mov_b32_dpp v108, v120 row_shr:1 row_mask:0xf bank_mask:0xf
	v_mov_b32_dpp v109, v121 row_shr:1 row_mask:0xf bank_mask:0xf
	v_mov_b32_dpp v116, v118 row_shr:1 row_mask:0xf bank_mask:0xf
	v_mov_b32_dpp v117, v119 row_shr:1 row_mask:0xf bank_mask:0xf
	s_nop 1
	v_lshlrev_b32_e32 v82, 16, v84
	v_and_b32_e32 v83, 0xffff0000, v84
	v_lshlrev_b32_e32 v84, 16, v85
	v_and_b32_e32 v85, 0xffff0000, v85
	v_lshlrev_b32_e32 v106, 16, v108
	v_and_b32_e32 v107, 0xffff0000, v108
	v_lshlrev_b32_e32 v108, 16, v109
	v_and_b32_e32 v109, 0xffff0000, v109
	v_lshlrev_b32_e32 v114, 16, v116
	v_and_b32_e32 v115, 0xffff0000, v116
	v_lshlrev_b32_e32 v116, 16, v117
	v_and_b32_e32 v117, 0xffff0000, v117
	s_mov_b64 s[20:21], exec
	s_andn2_b64 exec, exec, s[42:43]
	v_mov_b32_e32 v85, 0
	v_mov_b32_e32 v84, 0
	v_mov_b32_e32 v83, 0
	v_mov_b32_e32 v82, 0
	v_mov_b32_e32 v109, 0
	v_mov_b32_e32 v108, 0
	v_mov_b32_e32 v107, 0
	v_mov_b32_e32 v106, 0
	v_mov_b32_e32 v117, 0
	v_mov_b32_e32 v116, 0
	v_mov_b32_e32 v115, 0
	v_mov_b32_e32 v114, 0
	s_mov_b64 exec, s[20:21]

.LBB0_470:
	s_andn2_saveexec_b64 s[0:1], s[0:1]
	s_cbranch_execz .LBB0_474
	ds_read_b64 v[22:23], v218 offset:96
	ds_read_b64 v[98:99], v218 offset:1120
	ds_read_b64 v[100:101], v218 offset:2144
	s_waitcnt lgkmcnt(0)
	v_mov_b32_dpp v22, v140 row_shr:1 row_mask:0xf bank_mask:0xf
	v_mov_b32_dpp v23, v141 row_shr:1 row_mask:0xf bank_mask:0xf
	v_mov_b32_dpp v98, v138 row_shr:1 row_mask:0xf bank_mask:0xf
	v_mov_b32_dpp v99, v139 row_shr:1 row_mask:0xf bank_mask:0xf
	v_mov_b32_dpp v100, v136 row_shr:1 row_mask:0xf bank_mask:0xf
	v_mov_b32_dpp v101, v137 row_shr:1 row_mask:0xf bank_mask:0xf
	s_nop 1
	v_lshlrev_b32_e32 v20, 16, v22
	v_and_b32_e32 v21, 0xffff0000, v22
	v_lshlrev_b32_e32 v22, 16, v23
	v_and_b32_e32 v23, 0xffff0000, v23
	v_lshlrev_b32_e32 v110, 16, v98
	v_and_b32_e32 v111, 0xffff0000, v98
	v_lshlrev_b32_e32 v112, 16, v99
	v_and_b32_e32 v113, 0xffff0000, v99
	v_lshlrev_b32_e32 v98, 16, v100
	v_and_b32_e32 v99, 0xffff0000, v100
	v_lshlrev_b32_e32 v100, 16, v101
	v_and_b32_e32 v101, 0xffff0000, v101
	s_mov_b64 s[20:21], exec
	s_andn2_b64 exec, exec, s[42:43]
	v_mov_b32_e32 v23, 0
	v_mov_b32_e32 v22, 0
	v_mov_b32_e32 v21, 0
	v_mov_b32_e32 v20, 0
	v_mov_b32_e32 v113, 0
	v_mov_b32_e32 v112, 0
	v_mov_b32_e32 v111, 0
	v_mov_b32_e32 v110, 0
	v_mov_b32_e32 v101, 0
	v_mov_b32_e32 v100, 0
	v_mov_b32_e32 v99, 0
	v_mov_b32_e32 v98, 0
	s_mov_b64 exec, s[20:21]

.LBB0_497:
	s_or_b64 exec, exec, s[56:57]
	s_waitcnt lgkmcnt(0)
	s_barrier
	s_and_saveexec_b64 s[0:1], s[38:39]
	s_cbranch_execz .LBB0_325
	s_mov_b64 s[20:21], src_shared_base
	s_cmp_lg_u32 s24, -1
	s_cselect_b32 s2, s24, 0
	s_cselect_b32 s20, s21, 0
	v_mov_b32_e32 v0, s2
	v_mov_b32_e32 v1, s20
	v_readfirstlane_b32 s20, v206
	s_cmpk_lt_u32 s20, 0x408
	s_cbranch_scc1 .Lmy_q_nowait
	s_waitcnt vmcnt(0)
.Lmy_q_nowait:
	ds_write_b32 v0, v205
	s_nop 0
	s_branch .LBB0_325
